# v53 with the weight-conversion split moved: QKV-phase two-unit CUs convert 3 chunks each (not 4), all 84 five-unit FFN1 CUs convert the remaining 214 chunks (2-3 each) before the FFN1 barrier
# speedup vs baseline: 1.0098x; 1.0098x over previous
; #define LAS __attribute__((address_space(3)))
; __device__ __forceinline__ int opaque_tid() { int t; asm volatile("v_mov_b32 %0, %1" : "=v"(t) : "v"((int)threadIdx.x)); return t; }
; __global__ void __launch_bounds__(NTHREADS, 2) mega_fwd(Params P) {
;     ...
;         if (!lastl && bx >= 82) {
;             const int t_ = opaque_tid(), w_ = __builtin_amdgcn_readfirstlane(t_ >> 6);
;             for (int c = bx - 82; c < CV_L / 8; c += G - 82) conv_item(P, l + 1, c * 8 + w_, (LAS float*)(ldsl + w_ * 8448), t_ & 63);
.Lxc1:
	v_readlane_b32 s12, v253, 45
	v_mul_u32_u24_e32 v63, 0x84, v17
	v_or_b32_e32 v64, 8, v17
	v_or_b32_e32 v65, 16, v17
	v_or_b32_e32 v66, 24, v17
	v_lshl_add_u64 v[54:55], s[4:5], 0, v[2:3]
	s_lshl_b32 s3, s2, 5
	s_lshl_b32 s8, s2, 1
	v_add_u32_e32 v68, v62, v4
	v_readlane_b32 s9, v254, 4
	v_readlane_b32 s13, v253, 46
	v_readlane_b32 s14, v254, 7
	v_readlane_b32 s15, v254, 32
	v_readlane_b32 s16, v254, 33
	v_readlane_b32 s17, v254, 35
	s_movk_i32 s18, 0x7fff
	s_mov_b32 s19, 0xffff0000
	s_movk_i32 s20, 0x2400
	v_readlane_b32 s10, v253, 11
	v_readlane_b32 s11, v253, 12
	s_cmp_eq_u32 s101, 2
	s_cbranch_scc0 .Lxc2
	s_lshr_b32 s9, s100, 3
	s_movk_i32 s14, 84
	s_movk_i32 s15, 672
	s_movk_i32 s16, 21504
	s_movk_i32 s17, 1344
	s_movk_i32 s100, 736
	s_branch .Lxc3
.Lxc2:
	s_movk_i32 s100, 522

; #define LAS __attribute__((address_space(3)))
; __global__ void __launch_bounds__(NTHREADS, 2) mega_fwd(Params P) {
;     ...
;             for (int c = bx - 82; c < CV_L / 8; c += G - 82) conv_item(P, l + 1, c * 8 + w_, (LAS float*)(ldsl + w_ * 8448), t_ & 63);
.LBB0_349:
	s_add_i32 s9, s9, s14
	s_add_i32 s2, s2, s15
	s_add_i32 s3, s3, s16
	s_add_i32 s8, s8, s17
	s_cmp_lt_i32 s9, s100
	s_cbranch_scc0 .LBB0_393

; #define LAS __attribute__((address_space(3)))
; __device__ __forceinline__ int opaque_tid() { int t; asm volatile("v_mov_b32 %0, %1" : "=v"(t) : "v"((int)threadIdx.x)); return t; }
; __global__ void __launch_bounds__(NTHREADS, 2) mega_fwd(Params P) {
;     ...
;         if (!lastl && bx >= 82) {
;             const int t_ = opaque_tid(), w_ = __builtin_amdgcn_readfirstlane(t_ >> 6);
;             for (int c = bx - 82; c < CV_L / 8; c += G - 82) conv_item(P, l + 1, c * 8 + w_, (LAS float*)(ldsl + w_ * 8448), t_ & 63);
.LBB0_1114:
	v_readlane_b32 s100, v254, 57
	s_nop 3
	s_sub_i32 s100, s100, 0xac
	s_cmp_lt_u32 s100, 84
	s_cbranch_scc0 .Lxconv_skip
	v_readlane_b32 s14, v252, 9
	s_nop 3
	s_cmp_lg_u32 s14, 3
	s_cbranch_scc0 .Lxconv_skip
	s_addk_i32 s100, 522
	s_lshl_b32 s100, s100, 3
	s_mov_b32 s101, 2
	s_waitcnt vmcnt(0) lgkmcnt(0)
	s_barrier
	v_readlane_b32 s16, v253, 25
	v_readlane_b32 s26, v253, 35
	v_readlane_b32 s27, v253, 36
	v_readlane_b32 s28, v253, 37
	v_readlane_b32 s29, v253, 38
	v_readlane_b32 s17, v253, 26
	v_readlane_b32 s18, v253, 27
	v_readlane_b32 s19, v253, 28
	v_readlane_b32 s20, v253, 29
	v_readlane_b32 s21, v253, 30
	v_readlane_b32 s22, v253, 31
	v_readlane_b32 s23, v253, 32
	v_readlane_b32 s24, v253, 33
	v_readlane_b32 s25, v253, 34
	v_readlane_b32 s30, v253, 39
	v_readlane_b32 s31, v253, 40
	v_readlane_b32 s15, v252, 10
	v_mov_b32 v2, v214
	s_nop 0
	v_readfirstlane_b32 s0, v2
	s_nop 3
	s_branch .Lconv_entry
